# attention: WG-wide dynamic tile range (rigorous, bit-identical) with in-register wave reduction; prologue hoist
# speedup vs baseline: 1.0113x; 1.0051x over previous
.Ldyn_post:
	v_min_f32_e32 v246, v174, v175
	v_log_f32_e32 v246, v246
	v_sub_f32_e32 v247, s98, v182
	s_nop 0
	v_sub_f32_e32 v246, v247, v246
	v_max_f32_e32 v246, 0, v246
	s_nop 1
	v_max_f32_dpp v246, v246, v246 row_ror:8 row_mask:0xf bank_mask:0xf
	s_nop 1
	v_max_f32_dpp v246, v246, v246 row_ror:4 row_mask:0xf bank_mask:0xf
	s_nop 1
	v_max_f32_dpp v246, v246, v246 quad_perm:[2,3,0,1] row_mask:0xf bank_mask:0xf
	s_nop 1
	v_max_f32_dpp v246, v246, v246 quad_perm:[1,0,3,2] row_mask:0xf bank_mask:0xf
	v_mov_b32_e32 v247, v246
	s_nop 1
	v_permlane16_swap_b32_e32 v247, v246
	s_nop 0
	v_max_f32_e32 v246, v247, v246
	v_mov_b32_e32 v247, v246
	s_nop 1
	v_permlane32_swap_b32_e32 v247, v246
	s_nop 0
	v_max_f32_e32 v246, v247, v246
	v_mov_b32_e32 v247, 0x18080
	s_mov_b64 s[100:101], exec
	s_mov_b64 exec, 1
	ds_max_u32 v247, v246
	s_mov_b64 exec, s[100:101]
	s_waitcnt lgkmcnt(0)
	s_branch .Ldyn_post_back
